# context rows normalised at the end of the residual GEMM phases by workgroups 64..95 (split-K units signal completion through a counter, slabs written through): the norm phases and their barriers are g
# baseline (speedup 1.0000x reference)
.Lre0_split:
	s_lshl_b64 s[2:3], s[44:45], 2
	s_add_u32 s2, s2, s88
	s_addc_u32 s3, s3, s89
	s_waitcnt vmcnt(0)
	v_pk_mul_f32 v[126:127], v[126:127], v[134:135]
	v_pk_mul_f32 v[128:129], v[128:129], v[136:137]
	v_pk_mul_f32 v[122:123], v[122:123], v[130:131]
	v_pk_mul_f32 v[124:125], v[124:125], v[132:133]
	v_pk_mul_f32 v[118:119], v[118:119], v[134:135]
	v_pk_mul_f32 v[120:121], v[120:121], v[136:137]
	v_pk_mul_f32 v[114:115], v[114:115], v[130:131]
	v_pk_mul_f32 v[116:117], v[116:117], v[132:133]
	v_pk_mul_f32 v[110:111], v[110:111], v[134:135]
	v_pk_mul_f32 v[112:113], v[112:113], v[136:137]
	v_pk_mul_f32 v[106:107], v[106:107], v[130:131]
	v_pk_mul_f32 v[108:109], v[108:109], v[132:133]
	v_pk_mul_f32 v[102:103], v[102:103], v[134:135]
	v_pk_mul_f32 v[104:105], v[104:105], v[136:137]
	v_pk_mul_f32 v[98:99], v[98:99], v[130:131]
	v_pk_mul_f32 v[100:101], v[100:101], v[132:133]
	v_pk_mul_f32 v[94:95], v[94:95], v[134:135]
	v_pk_mul_f32 v[96:97], v[96:97], v[136:137]
	v_pk_mul_f32 v[90:91], v[90:91], v[130:131]
	v_pk_mul_f32 v[92:93], v[92:93], v[132:133]
	v_pk_mul_f32 v[86:87], v[86:87], v[134:135]
	v_pk_mul_f32 v[88:89], v[88:89], v[136:137]
	v_pk_mul_f32 v[82:83], v[82:83], v[130:131]
	v_pk_mul_f32 v[84:85], v[84:85], v[132:133]
	v_pk_mul_f32 v[78:79], v[78:79], v[134:135]
	v_pk_mul_f32 v[80:81], v[80:81], v[136:137]
	v_pk_mul_f32 v[74:75], v[74:75], v[130:131]
	v_pk_mul_f32 v[76:77], v[76:77], v[132:133]
	v_pk_mul_f32 v[70:71], v[70:71], v[134:135]
	v_pk_mul_f32 v[72:73], v[72:73], v[136:137]
	v_pk_mul_f32 v[66:67], v[66:67], v[130:131]
	v_pk_mul_f32 v[68:69], v[68:69], v[132:133]
	global_store_dwordx4 v178, v[126:129], s[2:3] offset:0 sc0 sc1
	global_store_dwordx4 v178, v[122:125], s[2:3] offset:64 sc0 sc1
	s_add_u32 s2, s2, 0x10000
	s_addc_u32 s3, s3, 0
	global_store_dwordx4 v178, v[118:121], s[2:3] offset:0 sc0 sc1
	global_store_dwordx4 v178, v[114:117], s[2:3] offset:64 sc0 sc1
	s_add_u32 s2, s2, 0x10000
	s_addc_u32 s3, s3, 0
	global_store_dwordx4 v178, v[110:113], s[2:3] offset:0 sc0 sc1
	global_store_dwordx4 v178, v[106:109], s[2:3] offset:64 sc0 sc1
	s_add_u32 s2, s2, 0x10000
	s_addc_u32 s3, s3, 0
	global_store_dwordx4 v178, v[102:105], s[2:3] offset:0 sc0 sc1
	global_store_dwordx4 v178, v[98:101], s[2:3] offset:64 sc0 sc1
	s_add_u32 s2, s2, 0x50000
	s_addc_u32 s3, s3, 0
	global_store_dwordx4 v178, v[94:97], s[2:3] offset:0 sc0 sc1
	global_store_dwordx4 v178, v[90:93], s[2:3] offset:64 sc0 sc1
	s_add_u32 s2, s2, 0x10000
	s_addc_u32 s3, s3, 0
	global_store_dwordx4 v178, v[86:89], s[2:3] offset:0 sc0 sc1
	global_store_dwordx4 v178, v[82:85], s[2:3] offset:64 sc0 sc1
	s_add_u32 s2, s2, 0x10000
	s_addc_u32 s3, s3, 0
	global_store_dwordx4 v178, v[78:81], s[2:3] offset:0 sc0 sc1
	global_store_dwordx4 v178, v[74:77], s[2:3] offset:64 sc0 sc1
	s_add_u32 s2, s2, 0x10000
	s_addc_u32 s3, s3, 0
	global_store_dwordx4 v178, v[70:73], s[2:3] offset:0 sc0 sc1
	global_store_dwordx4 v178, v[66:69], s[2:3] offset:64 sc0 sc1

.Lre1_split:
	s_lshl_b64 s[2:3], s[44:45], 2
	s_add_u32 s2, s2, s88
	s_addc_u32 s3, s3, s89
	s_waitcnt vmcnt(0)
	v_pk_mul_f32 v[62:63], v[62:63], v[134:135]
	v_pk_mul_f32 v[64:65], v[64:65], v[136:137]
	v_pk_mul_f32 v[58:59], v[58:59], v[130:131]
	v_pk_mul_f32 v[60:61], v[60:61], v[132:133]
	v_pk_mul_f32 v[54:55], v[54:55], v[134:135]
	v_pk_mul_f32 v[56:57], v[56:57], v[136:137]
	v_pk_mul_f32 v[50:51], v[50:51], v[130:131]
	v_pk_mul_f32 v[52:53], v[52:53], v[132:133]
	v_pk_mul_f32 v[46:47], v[46:47], v[134:135]
	v_pk_mul_f32 v[48:49], v[48:49], v[136:137]
	v_pk_mul_f32 v[42:43], v[42:43], v[130:131]
	v_pk_mul_f32 v[44:45], v[44:45], v[132:133]
	v_pk_mul_f32 v[38:39], v[38:39], v[134:135]
	v_pk_mul_f32 v[40:41], v[40:41], v[136:137]
	v_pk_mul_f32 v[34:35], v[34:35], v[130:131]
	v_pk_mul_f32 v[36:37], v[36:37], v[132:133]
	v_pk_mul_f32 v[30:31], v[30:31], v[134:135]
	v_pk_mul_f32 v[32:33], v[32:33], v[136:137]
	v_pk_mul_f32 v[26:27], v[26:27], v[130:131]
	v_pk_mul_f32 v[28:29], v[28:29], v[132:133]
	v_pk_mul_f32 v[22:23], v[22:23], v[134:135]
	v_pk_mul_f32 v[24:25], v[24:25], v[136:137]
	v_pk_mul_f32 v[18:19], v[18:19], v[130:131]
	v_pk_mul_f32 v[20:21], v[20:21], v[132:133]
	v_pk_mul_f32 v[14:15], v[14:15], v[134:135]
	v_pk_mul_f32 v[16:17], v[16:17], v[136:137]
	v_pk_mul_f32 v[10:11], v[10:11], v[130:131]
	v_pk_mul_f32 v[12:13], v[12:13], v[132:133]
	v_pk_mul_f32 v[6:7], v[6:7], v[134:135]
	v_pk_mul_f32 v[8:9], v[8:9], v[136:137]
	v_pk_mul_f32 v[2:3], v[2:3], v[130:131]
	v_pk_mul_f32 v[4:5], v[4:5], v[132:133]
	global_store_dwordx4 v178, v[62:65], s[2:3] offset:512 sc0 sc1
	global_store_dwordx4 v178, v[58:61], s[2:3] offset:576 sc0 sc1
	s_add_u32 s2, s2, 0x10000
	s_addc_u32 s3, s3, 0
	global_store_dwordx4 v178, v[54:57], s[2:3] offset:512 sc0 sc1
	global_store_dwordx4 v178, v[50:53], s[2:3] offset:576 sc0 sc1
	s_add_u32 s2, s2, 0x10000
	s_addc_u32 s3, s3, 0
	global_store_dwordx4 v178, v[46:49], s[2:3] offset:512 sc0 sc1
	global_store_dwordx4 v178, v[42:45], s[2:3] offset:576 sc0 sc1
	s_add_u32 s2, s2, 0x10000
	s_addc_u32 s3, s3, 0
	global_store_dwordx4 v178, v[38:41], s[2:3] offset:512 sc0 sc1
	global_store_dwordx4 v178, v[34:37], s[2:3] offset:576 sc0 sc1
	s_add_u32 s2, s2, 0x50000
	s_addc_u32 s3, s3, 0
	global_store_dwordx4 v178, v[30:33], s[2:3] offset:512 sc0 sc1
	global_store_dwordx4 v178, v[26:29], s[2:3] offset:576 sc0 sc1
	s_add_u32 s2, s2, 0x10000
	s_addc_u32 s3, s3, 0
	global_store_dwordx4 v178, v[22:25], s[2:3] offset:512 sc0 sc1
	global_store_dwordx4 v178, v[18:21], s[2:3] offset:576 sc0 sc1
	s_add_u32 s2, s2, 0x10000
	s_addc_u32 s3, s3, 0
	global_store_dwordx4 v178, v[14:17], s[2:3] offset:512 sc0 sc1
	global_store_dwordx4 v178, v[10:13], s[2:3] offset:576 sc0 sc1
	s_add_u32 s2, s2, 0x10000
	s_addc_u32 s3, s3, 0
	global_store_dwordx4 v178, v[6:9], s[2:3] offset:512 sc0 sc1
	global_store_dwordx4 v178, v[2:5], s[2:3] offset:576 sc0 sc1

.Lfz_skip:
	s_and_b64 vcc, exec, s[34:35]
	s_cbranch_vccnz .Lfz_nosig
	s_waitcnt vmcnt(0)
	v_readlane_b32 s2, v255, 14
	s_cmp_eq_u32 s2, 5
	s_movk_i32 s2, 0x3e40
	s_cselect_b32 s2, 0x3e00, s2
	s_add_u32 s2, s8, s2
	s_addc_u32 s3, s9, 0
	s_mov_b64 s[12:13], exec
	s_mov_b64 exec, 1
	v_mov_b32_e32 v130, 0
	v_mov_b32_e32 v131, 1
	s_nop 1
	global_atomic_add v130, v131, s[2:3]
	s_mov_b64 exec, s[12:13]

.LBB0_194:
	v_readlane_b32 s0, v252, 2
	s_cmp_eq_u32 s0, 0x100
	s_cbranch_scc0 .Lcx_skip
	v_readlane_b32 s1, v255, 14
	v_readlane_b32 s2, v255, 12
	s_cmp_lt_u32 s2, 3
	s_cbranch_scc0 .Lcx_skip
	s_cmp_eq_u32 s1, 5
	s_cbranch_scc1 .Lcx_go
	s_cmp_eq_u32 s1, 8
	s_cbranch_scc0 .Lcx_skip
.Lcx_go:
	v_readlane_b32 s3, v254, 58
	s_sub_u32 s3, s3, 64
	s_cmp_lt_u32 s3, 32
	s_cbranch_scc0 .Lcx_skip
	v_readfirstlane_b32 s12, v202
	s_lshr_b32 s12, s12, 6
	s_lshl_b32 s84, s3, 3
	s_add_i32 s84, s84, s12
	v_and_b32_e32 v197, 63, v202
	v_lshlrev_b32_e32 v190, 4, v197
	v_lshlrev_b32_e32 v191, 3, v197
	v_mov_b32_e32 v193, 0
	s_cmp_eq_u32 s1, 5
	s_cselect_b32 s85, 0, 1
	s_movk_i32 s88, 352
	s_cselect_b32 s88, 128, s88
	s_cselect_b32 s89, 4, 11
	s_movk_i32 s3, 0x3e40
	s_cselect_b32 s3, 0x3e00, s3
	s_add_i32 s86, s2, s85
	s_add_i32 s87, s2, 1
	s_mul_i32 s88, s88, s87
	s_add_u32 s18, s8, s3
	s_addc_u32 s19, s9, 0
	v_readlane_b32 s12, v254, 21
	v_readlane_b32 s13, v254, 22
	v_readlane_b32 s14, v254, 54
	v_readlane_b32 s15, v254, 55
	s_cmp_eq_u32 s1, 5
	s_cselect_b32 s12, s12, s14
	s_cselect_b32 s13, s13, s15
	s_cselect_b32 s3, 0x3000, 0
	s_lshl_b32 s14, s86, 12
	s_add_u32 s12, s12, s14
	s_addc_u32 s13, s13, 0
	v_readlane_b32 s16, v252, 11
	v_readlane_b32 s17, v252, 12
	s_mul_i32 s14, s86, 0xc000
	s_add_i32 s14, s14, s3
	s_add_i32 s14, s14, 0x6000
	s_add_u32 s16, s16, s14
	s_addc_u32 s17, s17, 0
	s_add_u32 s14, s16, 0x1000
	s_addc_u32 s15, s17, 0
	s_nop 1
	global_load_dwordx4 v[18:21], v190, s[12:13]
	global_load_dwordx4 v[34:37], v190, s[14:15]
	global_load_dwordx4 v[50:53], v190, s[16:17]
	global_load_dwordx4 v[22:25], v190, s[12:13] offset:1024
	global_load_dwordx4 v[38:41], v190, s[14:15] offset:1024
	global_load_dwordx4 v[54:57], v190, s[16:17] offset:1024
	global_load_dwordx4 v[26:29], v190, s[12:13] offset:2048
	global_load_dwordx4 v[42:45], v190, s[14:15] offset:2048
	global_load_dwordx4 v[58:61], v190, s[16:17] offset:2048
	global_load_dwordx4 v[30:33], v190, s[12:13] offset:3072
	global_load_dwordx4 v[46:49], v190, s[14:15] offset:3072
	global_load_dwordx4 v[62:65], v190, s[16:17] offset:3072
	v_readlane_b32 s40, v252, 5
	v_readlane_b32 s41, v252, 6
	s_lshl_b32 s3, s84, 12
	s_add_u32 s40, s40, s3
	s_addc_u32 s41, s41, 0
	s_add_u32 s40, s40, 0x4000000
	s_addc_u32 s41, s41, 0
	v_readlane_b32 s42, v254, 46
	v_readlane_b32 s43, v254, 47
	s_add_u32 s42, s42, s3
	s_addc_u32 s43, s43, 0
	s_cmp_eq_u32 s86, 0
	s_cselect_b32 s42, s42, s40
	s_cselect_b32 s43, s43, s41
	s_nop 1
	global_load_dwordx4 v[2:5], v190, s[42:43]
	global_load_dwordx4 v[6:9], v190, s[42:43] offset:1024
	global_load_dwordx4 v[10:13], v190, s[42:43] offset:2048
	global_load_dwordx4 v[14:17], v190, s[42:43] offset:3072
	s_add_u32 s44, s8, 0x16acc000
	s_addc_u32 s45, s9, 0
	s_add_u32 s44, s44, s3
	s_addc_u32 s45, s45, 0
	s_mov_b32 s3, 0
.Lcx_poll:
	global_load_dword v192, v193, s[18:19] sc1
	s_waitcnt vmcnt(0)
	v_readfirstlane_b32 s22, v192
	s_cmp_ge_u32 s22, s88
	s_cbranch_scc1 .Lcx_ready
	s_add_i32 s3, s3, 1
	s_cmp_lt_u32 s3, 0x4000
	s_cbranch_scc0 .Lcx_ready
	s_sleep 1
	s_branch .Lcx_poll
.Lcx_ready:
	global_load_dwordx4 v[70:73], v190, s[44:45] sc0 sc1
	global_load_dwordx4 v[74:77], v190, s[44:45] offset:1024 sc0 sc1
	global_load_dwordx4 v[78:81], v190, s[44:45] offset:2048 sc0 sc1
	global_load_dwordx4 v[82:85], v190, s[44:45] offset:3072 sc0 sc1
	s_add_u32 s44, s44, 0x100000
	s_addc_u32 s45, s45, 0
	global_load_dwordx4 v[86:89], v190, s[44:45] sc0 sc1
	global_load_dwordx4 v[90:93], v190, s[44:45] offset:1024 sc0 sc1
	global_load_dwordx4 v[94:97], v190, s[44:45] offset:2048 sc0 sc1
	global_load_dwordx4 v[98:101], v190, s[44:45] offset:3072 sc0 sc1
	s_add_u32 s44, s44, 0x100000
	s_addc_u32 s45, s45, 0
	global_load_dwordx4 v[102:105], v190, s[44:45] sc0 sc1
	global_load_dwordx4 v[106:109], v190, s[44:45] offset:1024 sc0 sc1
	global_load_dwordx4 v[110:113], v190, s[44:45] offset:2048 sc0 sc1
	global_load_dwordx4 v[114:117], v190, s[44:45] offset:3072 sc0 sc1
	s_add_u32 s44, s44, 0x100000
	s_addc_u32 s45, s45, 0
	global_load_dwordx4 v[118:121], v190, s[44:45] sc0 sc1
	global_load_dwordx4 v[122:125], v190, s[44:45] offset:1024 sc0 sc1
	global_load_dwordx4 v[126:129], v190, s[44:45] offset:2048 sc0 sc1
	global_load_dwordx4 v[130:133], v190, s[44:45] offset:3072 sc0 sc1
	s_add_u32 s44, s44, 0x100000
	s_addc_u32 s45, s45, 0
	s_waitcnt vmcnt(0)
	v_add_f32_e32 v2, v2, v70
	v_add_f32_e32 v3, v3, v71
	v_add_f32_e32 v4, v4, v72
	v_add_f32_e32 v5, v5, v73
	v_add_f32_e32 v6, v6, v74
	v_add_f32_e32 v7, v7, v75
	v_add_f32_e32 v8, v8, v76
	v_add_f32_e32 v9, v9, v77
	v_add_f32_e32 v10, v10, v78
	v_add_f32_e32 v11, v11, v79
	v_add_f32_e32 v12, v12, v80
	v_add_f32_e32 v13, v13, v81
	v_add_f32_e32 v14, v14, v82
	v_add_f32_e32 v15, v15, v83
	v_add_f32_e32 v16, v16, v84
	v_add_f32_e32 v17, v17, v85
	v_add_f32_e32 v2, v2, v86
	v_add_f32_e32 v3, v3, v87
	v_add_f32_e32 v4, v4, v88
	v_add_f32_e32 v5, v5, v89
	v_add_f32_e32 v6, v6, v90
	v_add_f32_e32 v7, v7, v91
	v_add_f32_e32 v8, v8, v92
	v_add_f32_e32 v9, v9, v93
	v_add_f32_e32 v10, v10, v94
	v_add_f32_e32 v11, v11, v95
	v_add_f32_e32 v12, v12, v96
	v_add_f32_e32 v13, v13, v97
	v_add_f32_e32 v14, v14, v98
	v_add_f32_e32 v15, v15, v99
	v_add_f32_e32 v16, v16, v100
	v_add_f32_e32 v17, v17, v101
	v_add_f32_e32 v2, v2, v102
	v_add_f32_e32 v3, v3, v103
	v_add_f32_e32 v4, v4, v104
	v_add_f32_e32 v5, v5, v105
	v_add_f32_e32 v6, v6, v106
	v_add_f32_e32 v7, v7, v107
	v_add_f32_e32 v8, v8, v108
	v_add_f32_e32 v9, v9, v109
	v_add_f32_e32 v10, v10, v110
	v_add_f32_e32 v11, v11, v111
	v_add_f32_e32 v12, v12, v112
	v_add_f32_e32 v13, v13, v113
	v_add_f32_e32 v14, v14, v114
	v_add_f32_e32 v15, v15, v115
	v_add_f32_e32 v16, v16, v116
	v_add_f32_e32 v17, v17, v117
	v_add_f32_e32 v2, v2, v118
	v_add_f32_e32 v3, v3, v119
	v_add_f32_e32 v4, v4, v120
	v_add_f32_e32 v5, v5, v121
	v_add_f32_e32 v6, v6, v122
	v_add_f32_e32 v7, v7, v123
	v_add_f32_e32 v8, v8, v124
	v_add_f32_e32 v9, v9, v125
	v_add_f32_e32 v10, v10, v126
	v_add_f32_e32 v11, v11, v127
	v_add_f32_e32 v12, v12, v128
	v_add_f32_e32 v13, v13, v129
	v_add_f32_e32 v14, v14, v130
	v_add_f32_e32 v15, v15, v131
	v_add_f32_e32 v16, v16, v132
	v_add_f32_e32 v17, v17, v133
	s_cmp_eq_u32 s89, 4
	s_cbranch_scc1 .Lcx_summed
	global_load_dwordx4 v[70:73], v190, s[44:45] sc0 sc1
	global_load_dwordx4 v[74:77], v190, s[44:45] offset:1024 sc0 sc1
	global_load_dwordx4 v[78:81], v190, s[44:45] offset:2048 sc0 sc1
	global_load_dwordx4 v[82:85], v190, s[44:45] offset:3072 sc0 sc1
	s_add_u32 s44, s44, 0x100000
	s_addc_u32 s45, s45, 0
	global_load_dwordx4 v[86:89], v190, s[44:45] sc0 sc1
	global_load_dwordx4 v[90:93], v190, s[44:45] offset:1024 sc0 sc1
	global_load_dwordx4 v[94:97], v190, s[44:45] offset:2048 sc0 sc1
	global_load_dwordx4 v[98:101], v190, s[44:45] offset:3072 sc0 sc1
	s_add_u32 s44, s44, 0x100000
	s_addc_u32 s45, s45, 0
	global_load_dwordx4 v[102:105], v190, s[44:45] sc0 sc1
	global_load_dwordx4 v[106:109], v190, s[44:45] offset:1024 sc0 sc1
	global_load_dwordx4 v[110:113], v190, s[44:45] offset:2048 sc0 sc1
	global_load_dwordx4 v[114:117], v190, s[44:45] offset:3072 sc0 sc1
	s_add_u32 s44, s44, 0x100000
	s_addc_u32 s45, s45, 0
	global_load_dwordx4 v[118:121], v190, s[44:45] sc0 sc1
	global_load_dwordx4 v[122:125], v190, s[44:45] offset:1024 sc0 sc1
	global_load_dwordx4 v[126:129], v190, s[44:45] offset:2048 sc0 sc1
	global_load_dwordx4 v[130:133], v190, s[44:45] offset:3072 sc0 sc1
	s_add_u32 s44, s44, 0x100000
	s_addc_u32 s45, s45, 0
	s_waitcnt vmcnt(0)
	v_add_f32_e32 v2, v2, v70
	v_add_f32_e32 v3, v3, v71
	v_add_f32_e32 v4, v4, v72
	v_add_f32_e32 v5, v5, v73
	v_add_f32_e32 v6, v6, v74
	v_add_f32_e32 v7, v7, v75
	v_add_f32_e32 v8, v8, v76
	v_add_f32_e32 v9, v9, v77
	v_add_f32_e32 v10, v10, v78
	v_add_f32_e32 v11, v11, v79
	v_add_f32_e32 v12, v12, v80
	v_add_f32_e32 v13, v13, v81
	v_add_f32_e32 v14, v14, v82
	v_add_f32_e32 v15, v15, v83
	v_add_f32_e32 v16, v16, v84
	v_add_f32_e32 v17, v17, v85
	v_add_f32_e32 v2, v2, v86
	v_add_f32_e32 v3, v3, v87
	v_add_f32_e32 v4, v4, v88
	v_add_f32_e32 v5, v5, v89
	v_add_f32_e32 v6, v6, v90
	v_add_f32_e32 v7, v7, v91
	v_add_f32_e32 v8, v8, v92
	v_add_f32_e32 v9, v9, v93
	v_add_f32_e32 v10, v10, v94
	v_add_f32_e32 v11, v11, v95
	v_add_f32_e32 v12, v12, v96
	v_add_f32_e32 v13, v13, v97
	v_add_f32_e32 v14, v14, v98
	v_add_f32_e32 v15, v15, v99
	v_add_f32_e32 v16, v16, v100
	v_add_f32_e32 v17, v17, v101
	v_add_f32_e32 v2, v2, v102
	v_add_f32_e32 v3, v3, v103
	v_add_f32_e32 v4, v4, v104
	v_add_f32_e32 v5, v5, v105
	v_add_f32_e32 v6, v6, v106
	v_add_f32_e32 v7, v7, v107
	v_add_f32_e32 v8, v8, v108
	v_add_f32_e32 v9, v9, v109
	v_add_f32_e32 v10, v10, v110
	v_add_f32_e32 v11, v11, v111
	v_add_f32_e32 v12, v12, v112
	v_add_f32_e32 v13, v13, v113
	v_add_f32_e32 v14, v14, v114
	v_add_f32_e32 v15, v15, v115
	v_add_f32_e32 v16, v16, v116
	v_add_f32_e32 v17, v17, v117
	v_add_f32_e32 v2, v2, v118
	v_add_f32_e32 v3, v3, v119
	v_add_f32_e32 v4, v4, v120
	v_add_f32_e32 v5, v5, v121
	v_add_f32_e32 v6, v6, v122
	v_add_f32_e32 v7, v7, v123
	v_add_f32_e32 v8, v8, v124
	v_add_f32_e32 v9, v9, v125
	v_add_f32_e32 v10, v10, v126
	v_add_f32_e32 v11, v11, v127
	v_add_f32_e32 v12, v12, v128
	v_add_f32_e32 v13, v13, v129
	v_add_f32_e32 v14, v14, v130
	v_add_f32_e32 v15, v15, v131
	v_add_f32_e32 v16, v16, v132
	v_add_f32_e32 v17, v17, v133
	global_load_dwordx4 v[70:73], v190, s[44:45] sc0 sc1
	global_load_dwordx4 v[74:77], v190, s[44:45] offset:1024 sc0 sc1
	global_load_dwordx4 v[78:81], v190, s[44:45] offset:2048 sc0 sc1
	global_load_dwordx4 v[82:85], v190, s[44:45] offset:3072 sc0 sc1
	s_add_u32 s44, s44, 0x100000
	s_addc_u32 s45, s45, 0
	global_load_dwordx4 v[86:89], v190, s[44:45] sc0 sc1
	global_load_dwordx4 v[90:93], v190, s[44:45] offset:1024 sc0 sc1
	global_load_dwordx4 v[94:97], v190, s[44:45] offset:2048 sc0 sc1
	global_load_dwordx4 v[98:101], v190, s[44:45] offset:3072 sc0 sc1
	s_add_u32 s44, s44, 0x100000
	s_addc_u32 s45, s45, 0
	global_load_dwordx4 v[102:105], v190, s[44:45] sc0 sc1
	global_load_dwordx4 v[106:109], v190, s[44:45] offset:1024 sc0 sc1
	global_load_dwordx4 v[110:113], v190, s[44:45] offset:2048 sc0 sc1
	global_load_dwordx4 v[114:117], v190, s[44:45] offset:3072 sc0 sc1
	s_add_u32 s44, s44, 0x100000
	s_addc_u32 s45, s45, 0
	s_waitcnt vmcnt(0)
	v_add_f32_e32 v2, v2, v70
	v_add_f32_e32 v3, v3, v71
	v_add_f32_e32 v4, v4, v72
	v_add_f32_e32 v5, v5, v73
	v_add_f32_e32 v6, v6, v74
	v_add_f32_e32 v7, v7, v75
	v_add_f32_e32 v8, v8, v76
	v_add_f32_e32 v9, v9, v77
	v_add_f32_e32 v10, v10, v78
	v_add_f32_e32 v11, v11, v79
	v_add_f32_e32 v12, v12, v80
	v_add_f32_e32 v13, v13, v81
	v_add_f32_e32 v14, v14, v82
	v_add_f32_e32 v15, v15, v83
	v_add_f32_e32 v16, v16, v84
	v_add_f32_e32 v17, v17, v85
	v_add_f32_e32 v2, v2, v86
	v_add_f32_e32 v3, v3, v87
	v_add_f32_e32 v4, v4, v88
	v_add_f32_e32 v5, v5, v89
	v_add_f32_e32 v6, v6, v90
	v_add_f32_e32 v7, v7, v91
	v_add_f32_e32 v8, v8, v92
	v_add_f32_e32 v9, v9, v93
	v_add_f32_e32 v10, v10, v94
	v_add_f32_e32 v11, v11, v95
	v_add_f32_e32 v12, v12, v96
	v_add_f32_e32 v13, v13, v97
	v_add_f32_e32 v14, v14, v98
	v_add_f32_e32 v15, v15, v99
	v_add_f32_e32 v16, v16, v100
	v_add_f32_e32 v17, v17, v101
	v_add_f32_e32 v2, v2, v102
	v_add_f32_e32 v3, v3, v103
	v_add_f32_e32 v4, v4, v104
	v_add_f32_e32 v5, v5, v105
	v_add_f32_e32 v6, v6, v106
	v_add_f32_e32 v7, v7, v107
	v_add_f32_e32 v8, v8, v108
	v_add_f32_e32 v9, v9, v109
	v_add_f32_e32 v10, v10, v110
	v_add_f32_e32 v11, v11, v111
	v_add_f32_e32 v12, v12, v112
	v_add_f32_e32 v13, v13, v113
	v_add_f32_e32 v14, v14, v114
	v_add_f32_e32 v15, v15, v115
	v_add_f32_e32 v16, v16, v116
	v_add_f32_e32 v17, v17, v117
.Lcx_summed:
	global_store_dwordx4 v190, v[2:5], s[40:41]
	global_store_dwordx4 v190, v[6:9], s[40:41] offset:1024
	global_store_dwordx4 v190, v[10:13], s[40:41] offset:2048
	global_store_dwordx4 v190, v[14:17], s[40:41] offset:3072
	v_mul_f32_e32 v66, v2, v2
	v_fmac_f32_e32 v66, v3, v3
	v_fmac_f32_e32 v66, v4, v4
	v_fmac_f32_e32 v66, v5, v5
	v_fmac_f32_e32 v66, v6, v6
	v_fmac_f32_e32 v66, v7, v7
	v_fmac_f32_e32 v66, v8, v8
	v_fmac_f32_e32 v66, v9, v9
	v_fmac_f32_e32 v66, v10, v10
	v_fmac_f32_e32 v66, v11, v11
	v_fmac_f32_e32 v66, v12, v12
	v_fmac_f32_e32 v66, v13, v13
	v_fmac_f32_e32 v66, v14, v14
	v_fmac_f32_e32 v66, v15, v15
	v_fmac_f32_e32 v66, v16, v16
	v_fmac_f32_e32 v66, v17, v17
	s_nop 1
	v_add_f32_dpp v66, v66, v66 quad_perm:[1,0,3,2] row_mask:0xf bank_mask:0xf
	s_nop 1
	v_add_f32_dpp v66, v66, v66 quad_perm:[2,3,0,1] row_mask:0xf bank_mask:0xf
	s_nop 1
	v_add_f32_dpp v66, v66, v66 row_ror:4 row_mask:0xf bank_mask:0xf
	s_nop 1
	v_add_f32_dpp v66, v66, v66 row_ror:8 row_mask:0xf bank_mask:0xf
	s_nop 1
	v_add_f32_dpp v66, v66, v66 row_bcast:15 row_mask:0xa bank_mask:0xf
	s_nop 1
	v_add_f32_dpp v66, v66, v66 row_bcast:31 row_mask:0xc bank_mask:0xf
	s_nop 1
	v_readlane_b32 s3, v66, 63
	v_mov_b32_e32 v67, 0x3a800000
	s_nop 1
	v_fma_f32 v67, s3, v67, v203
	v_rsq_f32_e32 v67, v67
	v_add_f32_e32 v34, 1.0, v34
	v_add_f32_e32 v35, 1.0, v35
	v_add_f32_e32 v36, 1.0, v36
	v_add_f32_e32 v37, 1.0, v37
	v_add_f32_e32 v38, 1.0, v38
	v_add_f32_e32 v39, 1.0, v39
	v_add_f32_e32 v40, 1.0, v40
	v_add_f32_e32 v41, 1.0, v41
	v_add_f32_e32 v42, 1.0, v42
	v_add_f32_e32 v43, 1.0, v43
	v_add_f32_e32 v44, 1.0, v44
	v_add_f32_e32 v45, 1.0, v45
	v_add_f32_e32 v46, 1.0, v46
	v_add_f32_e32 v47, 1.0, v47
	v_add_f32_e32 v48, 1.0, v48
	v_add_f32_e32 v49, 1.0, v49
	v_mul_f32_e32 v18, v18, v34
	v_mul_f32_e32 v19, v19, v35
	v_mul_f32_e32 v20, v20, v36
	v_mul_f32_e32 v21, v21, v37
	v_mul_f32_e32 v22, v22, v38
	v_mul_f32_e32 v23, v23, v39
	v_mul_f32_e32 v24, v24, v40
	v_mul_f32_e32 v25, v25, v41
	v_mul_f32_e32 v26, v26, v42
	v_mul_f32_e32 v27, v27, v43
	v_mul_f32_e32 v28, v28, v44
	v_mul_f32_e32 v29, v29, v45
	v_mul_f32_e32 v30, v30, v46
	v_mul_f32_e32 v31, v31, v47
	v_mul_f32_e32 v32, v32, v48
	v_mul_f32_e32 v33, v33, v49
	v_mul_f32_e32 v2, v2, v67
	v_mul_f32_e32 v3, v3, v67
	v_mul_f32_e32 v4, v4, v67
	v_mul_f32_e32 v5, v5, v67
	v_mul_f32_e32 v6, v6, v67
	v_mul_f32_e32 v7, v7, v67
	v_mul_f32_e32 v8, v8, v67
	v_mul_f32_e32 v9, v9, v67
	v_mul_f32_e32 v10, v10, v67
	v_mul_f32_e32 v11, v11, v67
	v_mul_f32_e32 v12, v12, v67
	v_mul_f32_e32 v13, v13, v67
	v_mul_f32_e32 v14, v14, v67
	v_mul_f32_e32 v15, v15, v67
	v_mul_f32_e32 v16, v16, v67
	v_mul_f32_e32 v17, v17, v67
	v_fma_f32 v2, v2, v18, v50
	v_fma_f32 v3, v3, v19, v51
	v_fma_f32 v4, v4, v20, v52
	v_fma_f32 v5, v5, v21, v53
	v_fma_f32 v6, v6, v22, v54
	v_fma_f32 v7, v7, v23, v55
	v_fma_f32 v8, v8, v24, v56
	v_fma_f32 v9, v9, v25, v57
	v_fma_f32 v10, v10, v26, v58
	v_fma_f32 v11, v11, v27, v59
	v_fma_f32 v12, v12, v28, v60
	v_fma_f32 v13, v13, v29, v61
	v_fma_f32 v14, v14, v30, v62
	v_fma_f32 v15, v15, v31, v63
	v_fma_f32 v16, v16, v32, v64
	v_fma_f32 v17, v17, v33, v65
	v_readlane_b32 s12, v252, 20
	v_readlane_b32 s13, v252, 21
	s_add_i32 s3, s84, 16387
	s_lshl_b32 s3, s3, 11
	s_add_u32 s12, s12, s3
	s_addc_u32 s13, s13, 0
	v_cvt_pk_bf16_f32 v70, v2, v3
	v_cvt_pk_bf16_f32 v71, v4, v5
	global_store_dwordx2 v191, v[70:71], s[12:13]
	v_cvt_pk_bf16_f32 v72, v6, v7
	v_cvt_pk_bf16_f32 v73, v8, v9
	global_store_dwordx2 v191, v[72:73], s[12:13] offset:512
	v_cvt_pk_bf16_f32 v74, v10, v11
	v_cvt_pk_bf16_f32 v75, v12, v13
	global_store_dwordx2 v191, v[74:75], s[12:13] offset:1024
	v_cvt_pk_bf16_f32 v76, v14, v15
	v_cvt_pk_bf16_f32 v77, v16, v17
	global_store_dwordx2 v191, v[76:77], s[12:13] offset:1536

.LBB0_549:
.LBB0_550:
	s_add_i32 s10, s10, 1
	v_readlane_b32 s0, v252, 2
	s_cmp_eq_u32 s0, 0x100
	s_cselect_b32 s0, 37, -1
	s_cmp_eq_u32 s10, s0
	s_cselect_b32 s10, 38, s10
	v_readlane_b32 s0, v252, 2
	s_cmp_eq_u32 s0, 0x100
	s_cbranch_scc0 .Lnp_keep
	s_add_i32 s0, s10, -1
	s_mul_hi_u32 s1, s0, 0x38e38e39
	s_lshr_b32 s1, s1, 1
	s_mul_i32 s2, s1, 9
	s_sub_i32 s2, s0, s2
	s_cmp_eq_u32 s2, 6
	s_cbranch_scc1 .Lnp_skip
	s_cmp_eq_u32 s2, 0
	s_cbranch_scc0 .Lnp_keep
	s_cmp_eq_u32 s1, 0
	s_cbranch_scc1 .Lnp_keep

.Lnp_keep:
	s_cmp_ge_i32 s10, s11
	s_mov_b64 s[0:1], -1
	s_cbranch_scc0 .LBB0_551
	s_getpc_b64 s[98:99]
